# v35
# baseline (speedup 1.0000x reference)
.LBB0_195:
	v_max3_f32 v144, v80, v81, v82
	v_max3_f32 v145, v83, v84, v85
	v_max3_f32 v146, v86, v87, v88
	v_max3_f32 v147, v89, v90, v91
	v_max3_f32 v148, v92, v93, v94
	v_max3_f32 v149, v95, v64, v65
	v_max3_f32 v150, v66, v67, v68
	v_max3_f32 v151, v69, v70, v71
	v_max3_f32 v152, v72, v73, v74
	v_max3_f32 v153, v75, v76, v77
	v_max3_f32 v144, v144, v78, v79
	v_max3_f32 v145, v145, v146, v147
	v_max3_f32 v148, v148, v149, v150
	v_max3_f32 v151, v151, v152, v153
	v_max3_f32 v144, v144, v145, v148
	v_max_f32_e32 v144, v144, v151
	v_mov_b32_e32 v145, v144
	s_nop 1
	v_permlane32_swap_b32_e32 v144, v145
	v_max_f32_e32 v144, v144, v145
	v_sub_f32_e32 v145, v144, v186
	v_mul_f32_e32 v145, 0x3db504f3, v145
	v_cmp_ge_f32_e32 vcc, s87, v145
	v_max_f32_e32 v144, v186, v144
	v_sub_f32_e32 v145, v186, v144
	v_mul_f32_e32 v145, 0x3e0293ee, v145
	v_exp_f32_e32 v145, v145
	s_cmp_eq_u64 vcc, exec
	s_cselect_b64 s[0:1], -1, 0
	v_readfirstlane_b32 s27, v187
	s_nop 3
	s_cmpk_lt_u32 s27, 0x100
	s_cbranch_scc1 .Lg1b_hs1
	s_waitcnt lgkmcnt(0)
	s_barrier
	s_waitcnt vmcnt(0)
	v_cndmask_b32_e64 v193, v145, 1.0, s[0:1]
	v_cmp_gt_f32_e32 vcc, 1.0, v193
	s_waitcnt vmcnt(3)
	ds_write_b128 v181, v[128:131]
	s_waitcnt vmcnt(2)
	ds_write_b128 v182, v[132:135]
	s_cbranch_vccz .LBB0_199
	s_and_saveexec_b64 s[2:3], s[4:5]
	ds_write_b32 v175, v193 offset:128
	s_or_b64 exec, exec, s[2:3]
	s_waitcnt lgkmcnt(0)
	ds_read_b128 v[146:149], v174 offset:224
	ds_read_b128 v[150:153], v174 offset:192
	ds_read_b128 v[154:157], v174 offset:160
	ds_read_b128 v[194:197], v174 offset:128
	s_waitcnt lgkmcnt(3)
	v_pk_mul_f32 v[62:63], v[62:63], v[148:149]
	s_waitcnt lgkmcnt(2)
	v_pk_mul_f32 v[58:59], v[58:59], v[152:153]
	s_waitcnt lgkmcnt(1)
	v_pk_mul_f32 v[54:55], v[54:55], v[156:157]
	s_waitcnt lgkmcnt(0)
	v_pk_mul_f32 v[50:51], v[50:51], v[196:197]
	v_pk_mul_f32 v[60:61], v[60:61], v[146:147]
	v_pk_mul_f32 v[56:57], v[56:57], v[150:151]
	v_pk_mul_f32 v[52:53], v[52:53], v[154:155]
	v_pk_mul_f32 v[48:49], v[48:49], v[194:195]
	v_pk_mul_f32 v[46:47], v[46:47], v[148:149]
	v_pk_mul_f32 v[42:43], v[42:43], v[152:153]
	v_pk_mul_f32 v[38:39], v[38:39], v[156:157]
	v_pk_mul_f32 v[34:35], v[34:35], v[196:197]
	v_pk_mul_f32 v[44:45], v[44:45], v[146:147]
	v_pk_mul_f32 v[40:41], v[40:41], v[150:151]
	v_pk_mul_f32 v[36:37], v[36:37], v[154:155]
	v_pk_mul_f32 v[32:33], v[32:33], v[194:195]
	v_pk_mul_f32 v[30:31], v[30:31], v[148:149]
	v_pk_mul_f32 v[26:27], v[26:27], v[152:153]
	v_pk_mul_f32 v[22:23], v[22:23], v[156:157]
	v_pk_mul_f32 v[18:19], v[18:19], v[196:197]
	v_pk_mul_f32 v[28:29], v[28:29], v[146:147]
	v_pk_mul_f32 v[24:25], v[24:25], v[150:151]
	v_pk_mul_f32 v[20:21], v[20:21], v[154:155]
	v_pk_mul_f32 v[16:17], v[16:17], v[194:195]
	v_pk_mul_f32 v[14:15], v[14:15], v[148:149]
	v_pk_mul_f32 v[10:11], v[10:11], v[152:153]
	v_pk_mul_f32 v[6:7], v[6:7], v[156:157]
	v_pk_mul_f32 v[2:3], v[2:3], v[196:197]
	v_pk_mul_f32 v[12:13], v[12:13], v[146:147]
	v_pk_mul_f32 v[8:9], v[8:9], v[150:151]
	v_pk_mul_f32 v[4:5], v[4:5], v[154:155]
	v_pk_mul_f32 v[0:1], v[0:1], v[194:195]

.LBB0_203:
	v_max3_f32 v144, v80, v81, v82
	v_max3_f32 v145, v83, v84, v85
	v_max3_f32 v146, v86, v87, v88
	v_max3_f32 v147, v89, v90, v91
	v_max3_f32 v148, v92, v93, v94
	v_max3_f32 v149, v95, v64, v65
	v_max3_f32 v150, v66, v67, v68
	v_max3_f32 v151, v69, v70, v71
	v_max3_f32 v152, v72, v73, v74
	v_max3_f32 v153, v75, v76, v77
	v_max3_f32 v144, v144, v78, v79
	v_max3_f32 v145, v145, v146, v147
	v_max3_f32 v148, v148, v149, v150
	v_max3_f32 v151, v151, v152, v153
	v_max3_f32 v144, v144, v145, v148
	v_max_f32_e32 v144, v144, v151
	v_mov_b32_e32 v145, v144
	s_nop 1
	v_permlane32_swap_b32_e32 v144, v145
	v_max_f32_e32 v144, v144, v145
	v_sub_f32_e32 v145, v144, v186
	v_mul_f32_e32 v145, 0x3db504f3, v145
	v_cmp_ge_f32_e32 vcc, s87, v145
	s_cmp_eq_u64 vcc, exec
	s_cselect_b64 s[0:1], -1, 0
	s_andn2_b64 vcc, exec, s[2:3]
	v_readfirstlane_b32 s27, v187
	s_nop 3
	s_cmpk_lt_u32 s27, 0x100
	s_cbranch_scc1 .Lg1b_hs2
	s_waitcnt lgkmcnt(0)
	s_barrier
	s_cbranch_vccnz .LBB0_205
	s_waitcnt vmcnt(0)
	s_waitcnt vmcnt(3)
	ds_write_b128 v181, v[128:131] offset:16384
	s_waitcnt vmcnt(2)
	ds_write_b128 v182, v[132:135] offset:16384
.LBB0_205:
	s_waitcnt vmcnt(3)
	v_max_f32_e32 v128, v186, v144
	v_sub_f32_e32 v129, v186, v128
	v_mul_f32_e32 v129, 0x3e0293ee, v129
	v_exp_f32_e32 v129, v129
	s_nop 0
	v_cndmask_b32_e64 v192, v129, 1.0, s[0:1]
	v_cmp_gt_f32_e32 vcc, 1.0, v192
	s_cbranch_vccz .LBB0_209
	s_and_saveexec_b64 s[2:3], s[4:5]
	ds_write_b32 v175, v192 offset:128
	s_or_b64 exec, exec, s[2:3]
	s_waitcnt lgkmcnt(0)
	s_waitcnt vmcnt(2)
	ds_read_b128 v[130:133], v174 offset:224
	s_waitcnt vmcnt(1)
	ds_read_b128 v[134:137], v174 offset:192
	s_waitcnt vmcnt(0)
	ds_read_b128 v[138:141], v174 offset:160
	ds_read_b128 v[142:145], v174 offset:128
	s_waitcnt lgkmcnt(3)
	v_pk_mul_f32 v[62:63], v[62:63], v[132:133]
	s_waitcnt lgkmcnt(2)
	v_pk_mul_f32 v[58:59], v[58:59], v[136:137]
	s_waitcnt lgkmcnt(1)
	v_pk_mul_f32 v[54:55], v[54:55], v[140:141]
	s_waitcnt lgkmcnt(0)
	v_pk_mul_f32 v[50:51], v[50:51], v[144:145]
	v_pk_mul_f32 v[60:61], v[60:61], v[130:131]
	v_pk_mul_f32 v[56:57], v[56:57], v[134:135]
	v_pk_mul_f32 v[52:53], v[52:53], v[138:139]
	v_pk_mul_f32 v[48:49], v[48:49], v[142:143]
	v_pk_mul_f32 v[46:47], v[46:47], v[132:133]
	v_pk_mul_f32 v[42:43], v[42:43], v[136:137]
	v_pk_mul_f32 v[38:39], v[38:39], v[140:141]
	v_pk_mul_f32 v[34:35], v[34:35], v[144:145]
	v_pk_mul_f32 v[44:45], v[44:45], v[130:131]
	v_pk_mul_f32 v[40:41], v[40:41], v[134:135]
	v_pk_mul_f32 v[36:37], v[36:37], v[138:139]
	v_pk_mul_f32 v[32:33], v[32:33], v[142:143]
	v_pk_mul_f32 v[30:31], v[30:31], v[132:133]
	v_pk_mul_f32 v[26:27], v[26:27], v[136:137]
	v_pk_mul_f32 v[22:23], v[22:23], v[140:141]
	v_pk_mul_f32 v[18:19], v[18:19], v[144:145]
	v_pk_mul_f32 v[28:29], v[28:29], v[130:131]
	v_pk_mul_f32 v[24:25], v[24:25], v[134:135]
	v_pk_mul_f32 v[20:21], v[20:21], v[138:139]
	v_pk_mul_f32 v[16:17], v[16:17], v[142:143]
	v_pk_mul_f32 v[14:15], v[14:15], v[132:133]
	v_pk_mul_f32 v[10:11], v[10:11], v[136:137]
	v_pk_mul_f32 v[6:7], v[6:7], v[140:141]
	v_pk_mul_f32 v[2:3], v[2:3], v[144:145]
	v_pk_mul_f32 v[12:13], v[12:13], v[130:131]
	v_pk_mul_f32 v[8:9], v[8:9], v[134:135]
	v_pk_mul_f32 v[4:5], v[4:5], v[138:139]
	v_pk_mul_f32 v[0:1], v[0:1], v[142:143]

.Lg1b_hs2:
	v_max_f32_e32 v136, v186, v144
	v_sub_f32_e32 v137, v186, v136
	v_mul_f32_e32 v137, 0x3e0293ee, v137
	v_exp_f32_e32 v137, v137
	s_nop 0
	v_cndmask_b32_e64 v192, v137, 1.0, s[0:1]
	v_cmp_gt_f32_e32 vcc, 1.0, v192
	s_cbranch_vccz .Lg1b_209
	s_and_saveexec_b64 s[28:29], s[4:5]
	ds_write_b32 v175, v192 offset:128
	s_or_b64 exec, exec, s[28:29]
	s_waitcnt lgkmcnt(0)
	ds_read_b128 v[146:149], v174 offset:224
	ds_read_b128 v[150:153], v174 offset:192
	ds_read_b128 v[194:197], v174 offset:160
	ds_read_b128 v[206:209], v174 offset:128
	s_waitcnt lgkmcnt(3)
	v_pk_mul_f32 v[62:63], v[62:63], v[148:149]
	s_waitcnt lgkmcnt(2)
	v_pk_mul_f32 v[58:59], v[58:59], v[152:153]
	s_waitcnt lgkmcnt(1)
	v_pk_mul_f32 v[54:55], v[54:55], v[196:197]
	s_waitcnt lgkmcnt(0)
	v_pk_mul_f32 v[50:51], v[50:51], v[208:209]
	v_pk_mul_f32 v[60:61], v[60:61], v[146:147]
	v_pk_mul_f32 v[56:57], v[56:57], v[150:151]
	v_pk_mul_f32 v[52:53], v[52:53], v[194:195]
	v_pk_mul_f32 v[48:49], v[48:49], v[206:207]
	v_pk_mul_f32 v[46:47], v[46:47], v[148:149]
	v_pk_mul_f32 v[42:43], v[42:43], v[152:153]
	v_pk_mul_f32 v[38:39], v[38:39], v[196:197]
	v_pk_mul_f32 v[34:35], v[34:35], v[208:209]
	v_pk_mul_f32 v[44:45], v[44:45], v[146:147]
	v_pk_mul_f32 v[40:41], v[40:41], v[150:151]
	v_pk_mul_f32 v[36:37], v[36:37], v[194:195]
	v_pk_mul_f32 v[32:33], v[32:33], v[206:207]
	v_pk_mul_f32 v[30:31], v[30:31], v[148:149]
	v_pk_mul_f32 v[26:27], v[26:27], v[152:153]
	v_pk_mul_f32 v[22:23], v[22:23], v[196:197]
	v_pk_mul_f32 v[18:19], v[18:19], v[208:209]
	v_pk_mul_f32 v[28:29], v[28:29], v[146:147]
	v_pk_mul_f32 v[24:25], v[24:25], v[150:151]
	v_pk_mul_f32 v[20:21], v[20:21], v[194:195]
	v_pk_mul_f32 v[16:17], v[16:17], v[206:207]
	v_pk_mul_f32 v[14:15], v[14:15], v[148:149]
	v_pk_mul_f32 v[10:11], v[10:11], v[152:153]
	v_pk_mul_f32 v[6:7], v[6:7], v[196:197]
	v_pk_mul_f32 v[2:3], v[2:3], v[208:209]
	v_pk_mul_f32 v[12:13], v[12:13], v[146:147]
	v_pk_mul_f32 v[8:9], v[8:9], v[150:151]
	v_pk_mul_f32 v[4:5], v[4:5], v[194:195]
	v_pk_mul_f32 v[0:1], v[0:1], v[206:207]
